# grid barrier: non-leader workgroups poll the cross-XCD generation word directly (one hop fewer); on top of v_mov_b64 accumulator zeroing
# speedup vs baseline: 1.0120x; 1.0002x over previous
; __global__ void __launch_bounds__(NTHREADS, 2) mega(Params P) {
;     ...
;         if (ph > P.ph_lo && ph != 11 && ph != 23) grid.sync();
.Lxb_lrel:
	buffer_inv sc1
	s_waitcnt vmcnt(0)
	s_branch .Lxb_done
.Lxb_follower:
	v_mov_b32_e32 v0, 0x2100
	s_mov_b32 s4, 0

; template <class Epi, bool ALIGN_EPI = true, bool SP2 = true>
; DI void gemm_phase(LAS unsigned char* lds, const Gemm g, const StaticOrder& S, const Epi& E) {
;     ...
;         const bool has_next = S.next(ui + 1, nxt);
;         const char* nA = has_next ? (const char*)g.A + (size_t)nxt.pm * tstepA : cA; const char* nB = has_next ? (const char*)g.Bt + (size_t)nxt.pn * tstep : cB;
;         for (int t = 0; t < nt; t += 2) {
;             const bool last = (t == nt - 2);
;             const char* a1 = cA + (size_t)(t + 1) * kstep;
;             const char* a2 = last ? nA : cA + (size_t)(t + 2) * kstep; const char* b2 = last ? nB : cB + (size_t)(t + 2) * kstep;
;             const char* a3 = a2 + kstep; const char* b3 = b2 + kstep;
;     ...
; #pragma unroll
;         for (int a = 0; a < 2; ++a)
; #pragma unroll
;             for (int b = 0; b < 2; ++b)
; #pragma unroll
;                 for (int m = 0; m < 4; ++m)
; #pragma unroll
;                     for (int n = 0; n < 2; ++n) acc[a][b][m][n] = (f32x4){0.f, 0.f, 0.f, 0.f};
.LBB0_535:
	s_ashr_i32 s11, s10, 31
	s_lshl_b64 s[12:13], s[10:11], 19
	s_add_u32 s12, s94, s12
	s_addc_u32 s13, s95, s13
	s_and_b64 s[14:15], s[2:3], exec
	s_cselect_b32 s1, s13, s17
	s_cselect_b32 s11, s12, s16
	s_ashr_i32 s9, s8, 31
	s_lshl_b64 s[14:15], s[8:9], 19
	s_add_u32 s14, s26, s14
	s_addc_u32 s15, s34, s15
	s_and_b64 s[40:41], s[2:3], exec
	s_cselect_b32 s9, s15, s19
	s_cselect_b32 s38, s14, s18
	s_add_u32 s16, s16, 0x40080
	s_addc_u32 s17, s17, 0
	s_add_u32 vcc_lo, s18, 0x100
	v_mov_b32_e32 v0, 0
	s_addc_u32 vcc_hi, s19, 0
	s_mov_b32 s46, -2
	v_mov_b32_e32 v1, 0
	v_mov_b64_e32 v[2:3], 0
	v_mov_b64_e32 v[4:5], 0
	v_mov_b64_e32 v[6:7], 0
	v_mov_b64_e32 v[8:9], 0
	v_mov_b64_e32 v[10:11], 0
	v_mov_b64_e32 v[12:13], 0
	v_mov_b64_e32 v[14:15], 0
	v_mov_b64_e32 v[16:17], 0
	v_mov_b64_e32 v[18:19], 0
	v_mov_b64_e32 v[20:21], 0
	v_mov_b64_e32 v[22:23], 0
	v_mov_b64_e32 v[24:25], 0
	v_mov_b64_e32 v[26:27], 0
	v_mov_b64_e32 v[28:29], 0
	v_mov_b64_e32 v[30:31], 0
	v_mov_b64_e32 v[32:33], 0
	v_mov_b64_e32 v[34:35], 0
	v_mov_b64_e32 v[36:37], 0
	v_mov_b64_e32 v[38:39], 0
	v_mov_b64_e32 v[40:41], 0
	v_mov_b64_e32 v[42:43], 0
	v_mov_b64_e32 v[44:45], 0
	v_mov_b64_e32 v[46:47], 0
	v_mov_b64_e32 v[48:49], 0
	v_mov_b64_e32 v[50:51], 0
	v_mov_b64_e32 v[52:53], 0
	v_mov_b64_e32 v[54:55], 0
	v_mov_b64_e32 v[56:57], 0
	v_mov_b64_e32 v[58:59], 0
	v_mov_b64_e32 v[60:61], 0
	v_mov_b64_e32 v[62:63], 0
	v_mov_b64_e32 v[64:65], 0
	v_mov_b64_e32 v[66:67], 0
	v_mov_b64_e32 v[68:69], 0
	v_mov_b64_e32 v[70:71], 0
	v_mov_b64_e32 v[72:73], 0
	v_mov_b64_e32 v[74:75], 0
	v_mov_b64_e32 v[76:77], 0
	v_mov_b64_e32 v[78:79], 0
	v_mov_b64_e32 v[80:81], 0
	v_mov_b64_e32 v[82:83], 0
	v_mov_b64_e32 v[84:85], 0
	v_mov_b64_e32 v[86:87], 0
	v_mov_b64_e32 v[88:89], 0
	v_mov_b64_e32 v[90:91], 0
	v_mov_b64_e32 v[92:93], 0
	v_mov_b64_e32 v[94:95], 0
	v_mov_b64_e32 v[96:97], 0
	v_mov_b64_e32 v[98:99], 0
	v_mov_b64_e32 v[100:101], 0
	v_mov_b64_e32 v[102:103], 0
	v_mov_b64_e32 v[104:105], 0
	v_mov_b64_e32 v[106:107], 0
	v_mov_b64_e32 v[108:109], 0
	v_mov_b64_e32 v[110:111], 0
	v_mov_b64_e32 v[112:113], 0
	v_mov_b64_e32 v[114:115], 0
	v_mov_b64_e32 v[116:117], 0
	v_mov_b64_e32 v[118:119], 0
	v_mov_b64_e32 v[120:121], 0
	v_mov_b64_e32 v[122:123], 0
	v_mov_b64_e32 v[124:125], 0
	v_mov_b64_e32 v[126:127], 0

; template <class Epi, bool ALIGN_EPI = true, bool SP2 = true>
; DI void gemm_phase(LAS unsigned char* lds, const Gemm g, const StaticOrder& S, const Epi& E) {
;     ...
;         const bool has_next = S.next(ui + 1, nxt);
;         const char* nA = has_next ? (const char*)g.A + (size_t)nxt.pm * tstepA : cA; const char* nB = has_next ? (const char*)g.Bt + (size_t)nxt.pn * tstep : cB;
;         for (int t = 0; t < nt; t += 2) {
;             const bool last = (t == nt - 2);
;             const char* a1 = cA + (size_t)(t + 1) * kstep;
;             const char* a2 = last ? nA : cA + (size_t)(t + 2) * kstep; const char* b2 = last ? nB : cB + (size_t)(t + 2) * kstep;
;             const char* a3 = a2 + kstep; const char* b3 = b2 + kstep;
;     ...
; #pragma unroll
;         for (int a = 0; a < 2; ++a)
; #pragma unroll
;             for (int b = 0; b < 2; ++b)
; #pragma unroll
;                 for (int m = 0; m < 4; ++m)
; #pragma unroll
;                     for (int n = 0; n < 2; ++n) acc[a][b][m][n] = (f32x4){0.f, 0.f, 0.f, 0.f};
.LBB0_590:
	s_ashr_i32 s19, s18, 31
	s_lshl_b64 s[40:41], s[18:19], 19
	s_add_u32 s44, s94, s40
	s_addc_u32 s45, s95, s41
	s_and_b64 s[40:41], s[2:3], exec
	s_cselect_b32 s19, s45, s5
	s_cselect_b32 s36, s44, s4
	s_ashr_i32 s17, s16, 31
	s_lshl_b64 s[40:41], s[16:17], 19
	s_add_u32 s46, s42, s40
	s_addc_u32 s47, s43, s41
	s_and_b64 s[40:41], s[2:3], exec
	s_cselect_b32 s17, s47, s7
	s_cselect_b32 s38, s46, s6
	s_add_u32 s4, s4, 0x40080
	s_addc_u32 s5, s5, 0
	s_add_u32 s70, s6, 0x100
	v_mov_b32_e32 v0, 0
	s_addc_u32 s72, s7, 0
	s_mov_b32 s81, -2
	v_mov_b32_e32 v1, 0
	v_mov_b64_e32 v[2:3], 0
	v_mov_b64_e32 v[4:5], 0
	v_mov_b64_e32 v[6:7], 0
	v_mov_b64_e32 v[8:9], 0
	v_mov_b64_e32 v[10:11], 0
	v_mov_b64_e32 v[12:13], 0
	v_mov_b64_e32 v[14:15], 0
	v_mov_b64_e32 v[16:17], 0
	v_mov_b64_e32 v[18:19], 0
	v_mov_b64_e32 v[20:21], 0
	v_mov_b64_e32 v[22:23], 0
	v_mov_b64_e32 v[24:25], 0
	v_mov_b64_e32 v[26:27], 0
	v_mov_b64_e32 v[28:29], 0
	v_mov_b64_e32 v[30:31], 0
	v_mov_b64_e32 v[32:33], 0
	v_mov_b64_e32 v[34:35], 0
	v_mov_b64_e32 v[36:37], 0
	v_mov_b64_e32 v[38:39], 0
	v_mov_b64_e32 v[40:41], 0
	v_mov_b64_e32 v[42:43], 0
	v_mov_b64_e32 v[44:45], 0
	v_mov_b64_e32 v[46:47], 0
	v_mov_b64_e32 v[48:49], 0
	v_mov_b64_e32 v[50:51], 0
	v_mov_b64_e32 v[52:53], 0
	v_mov_b64_e32 v[54:55], 0
	v_mov_b64_e32 v[56:57], 0
	v_mov_b64_e32 v[58:59], 0
	v_mov_b64_e32 v[60:61], 0
	v_mov_b64_e32 v[62:63], 0
	v_mov_b64_e32 v[64:65], 0
	v_mov_b64_e32 v[66:67], 0
	v_mov_b64_e32 v[68:69], 0
	v_mov_b64_e32 v[70:71], 0
	v_mov_b64_e32 v[72:73], 0
	v_mov_b64_e32 v[74:75], 0
	v_mov_b64_e32 v[76:77], 0
	v_mov_b64_e32 v[78:79], 0
	v_mov_b64_e32 v[80:81], 0
	v_mov_b64_e32 v[82:83], 0
	v_mov_b64_e32 v[84:85], 0
	v_mov_b64_e32 v[86:87], 0
	v_mov_b64_e32 v[88:89], 0
	v_mov_b64_e32 v[90:91], 0
	v_mov_b64_e32 v[92:93], 0
	v_mov_b64_e32 v[94:95], 0
	v_mov_b64_e32 v[96:97], 0
	v_mov_b64_e32 v[98:99], 0
	v_mov_b64_e32 v[100:101], 0
	v_mov_b64_e32 v[102:103], 0
	v_mov_b64_e32 v[104:105], 0
	v_mov_b64_e32 v[106:107], 0
	v_mov_b64_e32 v[108:109], 0
	v_mov_b64_e32 v[110:111], 0
	v_mov_b64_e32 v[112:113], 0
	v_mov_b64_e32 v[114:115], 0
	v_mov_b64_e32 v[116:117], 0
	v_mov_b64_e32 v[118:119], 0
	v_mov_b64_e32 v[120:121], 0
	v_mov_b64_e32 v[122:123], 0
	v_mov_b64_e32 v[124:125], 0
	v_mov_b64_e32 v[126:127], 0

; template <class Epi, bool ALIGN_EPI = true, bool SP2 = true>
; DI void gemm_phase(LAS unsigned char* lds, const Gemm g, const StaticOrder& S, const Epi& E) {
;     ...
; #pragma unroll
;         for (int a = 0; a < 2; ++a)
; #pragma unroll
;             for (int b = 0; b < 2; ++b)
; #pragma unroll
;                 for (int m = 0; m < 4; ++m)
; #pragma unroll
;                     for (int n = 0; n < 2; ++n) acc[a][b][m][n] = (f32x4){0.f, 0.f, 0.f, 0.f};
.LBB0_687:
	s_add_u32 vcc_lo, s40, 0x100
	s_addc_u32 vcc_hi, s41, 0
	s_add_u32 s55, s4, 0x100
	v_mov_b32_e32 v0, 0
	s_addc_u32 s73, s5, 0
	s_mov_b32 s4, 0
	v_mov_b32_e32 v1, 0
	v_mov_b64_e32 v[2:3], 0
	v_mov_b64_e32 v[4:5], 0
	v_mov_b64_e32 v[6:7], 0
	v_mov_b64_e32 v[8:9], 0
	v_mov_b64_e32 v[10:11], 0
	v_mov_b64_e32 v[12:13], 0
	v_mov_b64_e32 v[14:15], 0
	v_mov_b64_e32 v[16:17], 0
	v_mov_b64_e32 v[18:19], 0
	v_mov_b64_e32 v[20:21], 0
	v_mov_b64_e32 v[22:23], 0
	v_mov_b64_e32 v[24:25], 0
	v_mov_b64_e32 v[26:27], 0
	v_mov_b64_e32 v[28:29], 0
	v_mov_b64_e32 v[30:31], 0
	v_mov_b64_e32 v[32:33], 0
	v_mov_b64_e32 v[34:35], 0
	v_mov_b64_e32 v[36:37], 0
	v_mov_b64_e32 v[38:39], 0
	v_mov_b64_e32 v[40:41], 0
	v_mov_b64_e32 v[42:43], 0
	v_mov_b64_e32 v[44:45], 0
	v_mov_b64_e32 v[46:47], 0
	v_mov_b64_e32 v[48:49], 0
	v_mov_b64_e32 v[50:51], 0
	v_mov_b64_e32 v[52:53], 0
	v_mov_b64_e32 v[54:55], 0
	v_mov_b64_e32 v[56:57], 0
	v_mov_b64_e32 v[58:59], 0
	v_mov_b64_e32 v[60:61], 0
	v_mov_b64_e32 v[62:63], 0
	v_mov_b64_e32 v[64:65], 0
	v_mov_b64_e32 v[66:67], 0
	v_mov_b64_e32 v[68:69], 0
	v_mov_b64_e32 v[70:71], 0
	v_mov_b64_e32 v[72:73], 0
	v_mov_b64_e32 v[74:75], 0
	v_mov_b64_e32 v[76:77], 0
	v_mov_b64_e32 v[78:79], 0
	v_mov_b64_e32 v[80:81], 0
	v_mov_b64_e32 v[82:83], 0
	v_mov_b64_e32 v[84:85], 0
	v_mov_b64_e32 v[86:87], 0
	v_mov_b64_e32 v[88:89], 0
	v_mov_b64_e32 v[90:91], 0
	v_mov_b64_e32 v[92:93], 0
	v_mov_b64_e32 v[94:95], 0
	v_mov_b64_e32 v[96:97], 0
	v_mov_b64_e32 v[98:99], 0
	v_mov_b64_e32 v[100:101], 0
	v_mov_b64_e32 v[102:103], 0
	v_mov_b64_e32 v[104:105], 0
	v_mov_b64_e32 v[106:107], 0
	v_mov_b64_e32 v[108:109], 0
	v_mov_b64_e32 v[110:111], 0
	v_mov_b64_e32 v[112:113], 0
	v_mov_b64_e32 v[114:115], 0
	v_mov_b64_e32 v[116:117], 0
	v_mov_b64_e32 v[118:119], 0
	v_mov_b64_e32 v[120:121], 0
	v_mov_b64_e32 v[122:123], 0
	v_mov_b64_e32 v[124:125], 0
	v_mov_b64_e32 v[126:127], 0

; template <class Epi, bool ALIGN_EPI = true, bool SP2 = true>
; DI void gemm_phase(LAS unsigned char* lds, const Gemm g, const StaticOrder& S, const Epi& E) {
;     ...
;         const bool has_next = S.next(ui + 1, nxt);
;         const char* nA = has_next ? (const char*)g.A + (size_t)nxt.pm * tstepA : cA; const char* nB = has_next ? (const char*)g.Bt + (size_t)nxt.pn * tstep : cB;
;         for (int t = 0; t < nt; t += 2) {
;             const bool last = (t == nt - 2);
;             const char* a1 = cA + (size_t)(t + 1) * kstep;
;             const char* a2 = last ? nA : cA + (size_t)(t + 2) * kstep; const char* b2 = last ? nB : cB + (size_t)(t + 2) * kstep;
;             const char* a3 = a2 + kstep; const char* b3 = b2 + kstep;
;     ...
; #pragma unroll
;         for (int a = 0; a < 2; ++a)
; #pragma unroll
;             for (int b = 0; b < 2; ++b)
; #pragma unroll
;                 for (int m = 0; m < 4; ++m)
; #pragma unroll
;                     for (int n = 0; n < 2; ++n) acc[a][b][m][n] = (f32x4){0.f, 0.f, 0.f, 0.f};
.LBB0_769:
	s_ashr_i32 s9, s8, 31
	s_lshl_b64 s[10:11], s[8:9], 19
	s_add_u32 s10, s45, s10
	s_addc_u32 s11, s44, s11
	s_and_b64 s[12:13], s[2:3], exec
	s_cselect_b32 s9, s11, s15
	s_cselect_b32 s36, s10, s14
	s_ashr_i32 s7, s6, 31
	s_lshl_b64 s[12:13], s[6:7], 19
	s_add_u32 s12, s42, s12
	s_addc_u32 s13, s43, s13
	s_and_b64 s[18:19], s[2:3], exec
	s_cselect_b32 s7, s13, s17
	s_cselect_b32 s38, s12, s16
	s_add_u32 s14, s14, 0x40080
	s_addc_u32 s15, s15, 0
	s_add_u32 s70, s16, 0x100
	v_mov_b32_e32 v0, 0
	s_addc_u32 s72, s17, 0
	s_mov_b32 s81, -2
	v_mov_b32_e32 v1, 0
	v_mov_b64_e32 v[2:3], 0
	v_mov_b64_e32 v[4:5], 0
	v_mov_b64_e32 v[6:7], 0
	v_mov_b64_e32 v[8:9], 0
	v_mov_b64_e32 v[10:11], 0
	v_mov_b64_e32 v[12:13], 0
	v_mov_b64_e32 v[14:15], 0
	v_mov_b64_e32 v[16:17], 0
	v_mov_b64_e32 v[18:19], 0
	v_mov_b64_e32 v[20:21], 0
	v_mov_b64_e32 v[22:23], 0
	v_mov_b64_e32 v[24:25], 0
	v_mov_b64_e32 v[26:27], 0
	v_mov_b64_e32 v[28:29], 0
	v_mov_b64_e32 v[30:31], 0
	v_mov_b64_e32 v[32:33], 0
	v_mov_b64_e32 v[34:35], 0
	v_mov_b64_e32 v[36:37], 0
	v_mov_b64_e32 v[38:39], 0
	v_mov_b64_e32 v[40:41], 0
	v_mov_b64_e32 v[42:43], 0
	v_mov_b64_e32 v[44:45], 0
	v_mov_b64_e32 v[46:47], 0
	v_mov_b64_e32 v[48:49], 0
	v_mov_b64_e32 v[50:51], 0
	v_mov_b64_e32 v[52:53], 0
	v_mov_b64_e32 v[54:55], 0
	v_mov_b64_e32 v[56:57], 0
	v_mov_b64_e32 v[58:59], 0
	v_mov_b64_e32 v[60:61], 0
	v_mov_b64_e32 v[62:63], 0
	v_mov_b64_e32 v[64:65], 0
	v_mov_b64_e32 v[66:67], 0
	v_mov_b64_e32 v[68:69], 0
	v_mov_b64_e32 v[70:71], 0
	v_mov_b64_e32 v[72:73], 0
	v_mov_b64_e32 v[74:75], 0
	v_mov_b64_e32 v[76:77], 0
	v_mov_b64_e32 v[78:79], 0
	v_mov_b64_e32 v[80:81], 0
	v_mov_b64_e32 v[82:83], 0
	v_mov_b64_e32 v[84:85], 0
	v_mov_b64_e32 v[86:87], 0
	v_mov_b64_e32 v[88:89], 0
	v_mov_b64_e32 v[90:91], 0
	v_mov_b64_e32 v[92:93], 0
	v_mov_b64_e32 v[94:95], 0
	v_mov_b64_e32 v[96:97], 0
	v_mov_b64_e32 v[98:99], 0
	v_mov_b64_e32 v[100:101], 0
	v_mov_b64_e32 v[102:103], 0
	v_mov_b64_e32 v[104:105], 0
	v_mov_b64_e32 v[106:107], 0
	v_mov_b64_e32 v[108:109], 0
	v_mov_b64_e32 v[110:111], 0
	v_mov_b64_e32 v[112:113], 0
	v_mov_b64_e32 v[114:115], 0
	v_mov_b64_e32 v[116:117], 0
	v_mov_b64_e32 v[118:119], 0
	v_mov_b64_e32 v[120:121], 0
	v_mov_b64_e32 v[122:123], 0
	v_mov_b64_e32 v[124:125], 0
	v_mov_b64_e32 v[126:127], 0
